# LN-mix loop-top vmcnt(0) moved into the rare modulation-vector reload block (write-through stores get a full iteration to retire), on the router rewrite
# speedup vs baseline: 1.0039x; 1.0039x over previous
.LBB0_680:
	v_ashrrev_i32_e32 v112, 12, v114
	v_cmp_ne_u32_e32 vcc, v112, v158
	s_and_saveexec_b64 s[16:17], vcc
	s_cbranch_execz .LBB0_682
	v_mul_hi_i32_i24_e32 v33, 0x6000, v112
	v_mul_i32_i24_e32 v32, 0x6000, v112
	v_lshl_add_u64 v[32:33], v[116:117], 0, v[32:33]
	v_add_co_u32_e32 v56, vcc, 0x2000, v32
	v_mov_b32_e32 v158, v112
	s_nop 0
	v_addc_co_u32_e32 v57, vcc, 0, v33, vcc
	v_add_co_u32_e32 v58, vcc, 0x3000, v32
	s_nop 1
	v_addc_co_u32_e32 v59, vcc, 0, v33, vcc
	v_add_co_u32_e32 v68, vcc, 0x4000, v32
	s_nop 1
	v_addc_co_u32_e32 v69, vcc, 0, v33, vcc
	global_load_dwordx4 v[36:39], v[56:57], off
	global_load_dwordx4 v[52:55], v[56:57], off offset:1024
	global_load_dwordx4 v[44:47], v[58:59], off
	global_load_dwordx4 v[48:51], v[58:59], off offset:1024
	global_load_dwordx4 v[32:35], v[68:69], off
	global_load_dwordx4 v[40:43], v[68:69], off offset:1024
	global_load_dwordx4 v[64:67], v[56:57], off offset:2048
	global_load_dwordx4 v[76:79], v[56:57], off offset:3072
	global_load_dwordx4 v[60:63], v[58:59], off offset:2048
	global_load_dwordx4 v[72:75], v[58:59], off offset:3072
	s_nop 0
	global_load_dwordx4 v[56:59], v[68:69], off offset:2048
	s_nop 0
	global_load_dwordx4 v[68:71], v[68:69], off offset:3072
	s_waitcnt vmcnt(0)
.LBB0_682:
	s_or_b64 exec, exec, s[16:17]
	v_add_u32_e32 v128, 4, v114
	v_cmp_gt_i32_e32 vcc, s0, v128
	v_cmp_le_i32_e64 s[16:17], s0, v128
	v_mov_b64_e32 v[130:131], v[140:141]
	v_mov_b64_e32 v[132:133], v[138:139]
	v_mov_b64_e32 v[134:135], v[144:145]
	v_mov_b64_e32 v[136:137], v[142:143]
	v_mov_b32_e32 v93, v97
	v_mov_b32_e32 v95, v99
	v_mov_b32_e32 v88, v100
	v_mov_b32_e32 v89, v148
	v_mov_b32_e32 v80, v104
	v_mov_b32_e32 v81, v105
	v_mov_b32_e32 v82, v106
	v_mov_b32_e32 v83, v107
	v_mov_b32_e32 v91, v146
	v_mov_b32_e32 v94, v147
	v_mov_b32_e32 v90, v102
	v_mov_b32_e32 v92, v103
	v_mov_b32_e32 v86, v110
	v_mov_b32_e32 v87, v111
	v_mov_b32_e32 v84, v108
	v_mov_b32_e32 v85, v109
	s_and_saveexec_b64 s[24:25], vcc
	s_cbranch_execz .LBB0_684
	v_ashrrev_i32_e32 v129, 31, v128
	v_lshlrev_b64 v[80:81], 12, v[128:129]
	v_lshl_add_u64 v[92:93], v[118:119], 0, v[80:81]
	v_lshlrev_b64 v[80:81], 11, v[128:129]
	v_lshl_add_u64 v[130:131], v[120:121], 0, v[80:81]
	global_load_dwordx4 v[80:83], v[92:93], off nt
	global_load_dwordx4 v[84:87], v[92:93], off offset:1024 nt
	global_load_dwordx4 v[88:91], v[92:93], off offset:2048 nt
	s_nop 0
	global_load_dwordx4 v[92:95], v[92:93], off offset:3072 nt
	s_nop 0
	global_load_dwordx2 v[136:137], v[130:131], off
	global_load_dwordx2 v[134:135], v[130:131], off offset:512
	global_load_dwordx2 v[132:133], v[130:131], off offset:1024
	s_nop 0
	global_load_dwordx2 v[130:131], v[130:131], off offset:1536

.LBB0_1395:
	v_ashrrev_i32_e32 v112, 12, v114
	v_cmp_ne_u32_e32 vcc, v112, v158
	s_and_saveexec_b64 s[16:17], vcc
	s_cbranch_execz .LBB0_1397
	v_add_u32_e32 v32, 5, v112
	v_mul_hi_i32_i24_e32 v33, 0x6000, v32
	v_mul_i32_i24_e32 v32, 0x6000, v32
	v_lshl_add_u64 v[32:33], v[116:117], 0, v[32:33]
	v_add_co_u32_e32 v56, vcc, 0x2000, v32
	v_mov_b32_e32 v158, v112
	s_nop 0
	v_addc_co_u32_e32 v57, vcc, 0, v33, vcc
	v_add_co_u32_e32 v58, vcc, 0x3000, v32
	s_nop 1
	v_addc_co_u32_e32 v59, vcc, 0, v33, vcc
	v_add_co_u32_e32 v68, vcc, 0x4000, v32
	s_nop 1
	v_addc_co_u32_e32 v69, vcc, 0, v33, vcc
	global_load_dwordx4 v[36:39], v[56:57], off
	global_load_dwordx4 v[52:55], v[56:57], off offset:1024
	global_load_dwordx4 v[44:47], v[58:59], off
	global_load_dwordx4 v[48:51], v[58:59], off offset:1024
	global_load_dwordx4 v[32:35], v[68:69], off
	global_load_dwordx4 v[40:43], v[68:69], off offset:1024
	global_load_dwordx4 v[64:67], v[56:57], off offset:2048
	global_load_dwordx4 v[76:79], v[56:57], off offset:3072
	global_load_dwordx4 v[60:63], v[58:59], off offset:2048
	global_load_dwordx4 v[72:75], v[58:59], off offset:3072
	s_nop 0
	global_load_dwordx4 v[56:59], v[68:69], off offset:2048
	s_nop 0
	global_load_dwordx4 v[68:71], v[68:69], off offset:3072
	s_waitcnt vmcnt(0)
.LBB0_1397:
	s_or_b64 exec, exec, s[16:17]
	v_add_u32_e32 v128, 4, v114
	v_cmp_gt_i32_e32 vcc, s2, v128
	v_cmp_le_i32_e64 s[16:17], s2, v128
	v_mov_b64_e32 v[130:131], v[140:141]
	v_mov_b64_e32 v[132:133], v[138:139]
	v_mov_b64_e32 v[134:135], v[144:145]
	v_mov_b64_e32 v[136:137], v[142:143]
	v_mov_b32_e32 v93, v97
	v_mov_b32_e32 v95, v99
	v_mov_b32_e32 v88, v100
	v_mov_b32_e32 v89, v148
	v_mov_b32_e32 v80, v104
	v_mov_b32_e32 v81, v105
	v_mov_b32_e32 v82, v106
	v_mov_b32_e32 v83, v107
	v_mov_b32_e32 v91, v146
	v_mov_b32_e32 v94, v147
	v_mov_b32_e32 v90, v102
	v_mov_b32_e32 v92, v103
	v_mov_b32_e32 v86, v110
	v_mov_b32_e32 v87, v111
	v_mov_b32_e32 v84, v108
	v_mov_b32_e32 v85, v109
	s_and_saveexec_b64 s[26:27], vcc
	s_cbranch_execz .LBB0_1399
	v_ashrrev_i32_e32 v129, 31, v128
	v_lshlrev_b64 v[80:81], 12, v[128:129]
	v_lshl_add_u64 v[92:93], v[118:119], 0, v[80:81]
	v_lshlrev_b64 v[80:81], 11, v[128:129]
	v_lshl_add_u64 v[130:131], v[120:121], 0, v[80:81]
	global_load_dwordx4 v[80:83], v[92:93], off nt
	global_load_dwordx4 v[84:87], v[92:93], off offset:1024 nt
	global_load_dwordx4 v[88:91], v[92:93], off offset:2048 nt
	s_nop 0
	global_load_dwordx4 v[92:95], v[92:93], off offset:3072 nt
	s_nop 0
	global_load_dwordx2 v[136:137], v[130:131], off
	global_load_dwordx2 v[134:135], v[130:131], off offset:512
	global_load_dwordx2 v[132:133], v[130:131], off offset:1024
	s_nop 0
	global_load_dwordx2 v[130:131], v[130:131], off offset:1536
